# lora epilogue decay columns: exp(-exp(-softplus(-x)-0.5)) evaluated as exp(-e^-0.5/(1+exp(-x))), same function with 3 transcendentals
# baseline (speedup 1.0000x reference)
;     __device__ __forceinline__ void operator()(const f32x4 (&acc)[2][2][4][2], const pg8::Unit& u, int wr, int wc, int fr, int fq) const {
;     ...
;                     if (kind == 0) {
; #pragma unroll
;                         for (int i = 0; i < 4; ++i) {
;                             { const float z = -v0[i]; const float sp_ = fmaxf(z, 0.f) + __logf(1.f + __expf(-fabsf(z))); v0[i] = __expf(-__expf(-sp_ - 0.5f)); }
;                             { const float z = -v1[i]; const float sp_ = fmaxf(z, 0.f) + __logf(1.f + __expf(-fabsf(z))); v1[i] = __expf(-__expf(-sp_ - 0.5f)); }
;                         }
;                         *(f32x4*)(DEC + off) = v0; *(f32x4*)(DEC + off + 4) = v1;
.LBB0_453:
	s_and_b64 vcc, exec, s[2:3]
	s_cbranch_vccz .LBB0_455
	v_mul_f32_e32 v176, 0xbfb8aa3b, v170
	v_mul_f32_e32 v177, 0xbfb8aa3b, v171
	v_exp_f32_e32 v176, v176
	v_exp_f32_e32 v177, v177
	v_add_f32_e32 v176, 1.0, v176
	v_add_f32_e32 v177, 1.0, v177
	v_rcp_f32_e32 v176, v176
	v_rcp_f32_e32 v177, v177
	v_mul_f32_e32 v176, 0xbf60028b, v176
	v_mul_f32_e32 v177, 0xbf60028b, v177
	v_exp_f32_e32 v176, v176
	v_exp_f32_e32 v177, v177
	v_mul_f32_e32 v178, 0xbfb8aa3b, v130
	v_mul_f32_e32 v179, 0xbfb8aa3b, v131
	v_exp_f32_e32 v178, v178
	v_exp_f32_e32 v179, v179
	v_add_f32_e32 v178, 1.0, v178
	v_add_f32_e32 v179, 1.0, v179
	v_rcp_f32_e32 v178, v178
	v_rcp_f32_e32 v179, v179
	v_mul_f32_e32 v178, 0xbf60028b, v178
	v_mul_f32_e32 v179, 0xbf60028b, v179
	v_exp_f32_e32 v178, v178
	v_exp_f32_e32 v179, v179
	v_mul_f32_e32 v132, 0xbfb8aa3b, v132
	v_mul_f32_e32 v133, 0xbfb8aa3b, v133
	v_exp_f32_e32 v132, v132
	v_exp_f32_e32 v133, v133
	v_add_f32_e32 v132, 1.0, v132
	v_add_f32_e32 v133, 1.0, v133
	v_rcp_f32_e32 v132, v132
	v_rcp_f32_e32 v133, v133
	v_mul_f32_e32 v132, 0xbf60028b, v132
	v_mul_f32_e32 v133, 0xbf60028b, v133
	v_exp_f32_e32 v132, v132
	v_exp_f32_e32 v133, v133
	v_mul_f32_e32 v134, 0xbfb8aa3b, v128
	v_mul_f32_e32 v135, 0xbfb8aa3b, v129
	v_exp_f32_e32 v134, v134
	v_exp_f32_e32 v135, v135
	v_add_f32_e32 v134, 1.0, v134
	v_add_f32_e32 v135, 1.0, v135
	v_rcp_f32_e32 v134, v134
	v_rcp_f32_e32 v135, v135
	v_mul_f32_e32 v134, 0xbf60028b, v134
	v_mul_f32_e32 v135, 0xbf60028b, v135
	v_exp_f32_e32 v134, v134
	v_exp_f32_e32 v135, v135
	s_nop 0
	v_lshl_add_u64 v[128:129], v[168:169], 2, s[46:47]
	global_store_dwordx4 v[128:129], v[176:179], off
	global_store_dwordx4 v[128:129], v[132:135], off offset:16

;     __device__ __forceinline__ void operator()(const f32x4 (&acc)[2][2][4][2], const pg8::Unit& u, int wr, int wc, int fr, int fq) const {
;     ...
;                     if (kind == 0) {
; #pragma unroll
;                         for (int i = 0; i < 4; ++i) {
;                             { const float z = -v0[i]; const float sp_ = fmaxf(z, 0.f) + __logf(1.f + __expf(-fabsf(z))); v0[i] = __expf(-__expf(-sp_ - 0.5f)); }
;                             { const float z = -v1[i]; const float sp_ = fmaxf(z, 0.f) + __logf(1.f + __expf(-fabsf(z))); v1[i] = __expf(-__expf(-sp_ - 0.5f)); }
;                         }
;                         *(f32x4*)(DEC + off) = v0; *(f32x4*)(DEC + off + 4) = v1;
.LBB0_459:
	s_and_b64 vcc, exec, s[0:1]
	s_cbranch_vccz .LBB0_461
	v_mul_f32_e32 v124, 0xbfb8aa3b, v124
	v_mul_f32_e32 v125, 0xbfb8aa3b, v125
	v_exp_f32_e32 v124, v124
	v_exp_f32_e32 v125, v125
	v_add_f32_e32 v124, 1.0, v124
	v_add_f32_e32 v125, 1.0, v125
	v_rcp_f32_e32 v124, v124
	v_rcp_f32_e32 v125, v125
	v_mul_f32_e32 v124, 0xbf60028b, v124
	v_mul_f32_e32 v125, 0xbf60028b, v125
	v_exp_f32_e32 v124, v124
	v_exp_f32_e32 v125, v125
	v_mul_f32_e32 v126, 0xbfb8aa3b, v126
	v_mul_f32_e32 v127, 0xbfb8aa3b, v127
	v_exp_f32_e32 v126, v126
	v_exp_f32_e32 v127, v127
	v_add_f32_e32 v126, 1.0, v126
	v_add_f32_e32 v127, 1.0, v127
	v_rcp_f32_e32 v126, v126
	v_rcp_f32_e32 v127, v127
	v_mul_f32_e32 v126, 0xbf60028b, v126
	v_mul_f32_e32 v127, 0xbf60028b, v127
	v_exp_f32_e32 v126, v126
	v_exp_f32_e32 v127, v127
	v_mul_f32_e32 v120, 0xbfb8aa3b, v120
	v_mul_f32_e32 v121, 0xbfb8aa3b, v121
	v_exp_f32_e32 v120, v120
	v_exp_f32_e32 v121, v121
	v_add_f32_e32 v120, 1.0, v120
	v_add_f32_e32 v121, 1.0, v121
	v_rcp_f32_e32 v120, v120
	v_rcp_f32_e32 v121, v121
	v_mul_f32_e32 v120, 0xbf60028b, v120
	v_mul_f32_e32 v121, 0xbf60028b, v121
	v_exp_f32_e32 v120, v120
	v_exp_f32_e32 v121, v121
	v_mul_f32_e32 v122, 0xbfb8aa3b, v122
	v_mul_f32_e32 v123, 0xbfb8aa3b, v123
	v_exp_f32_e32 v122, v122
	v_exp_f32_e32 v123, v123
	v_add_f32_e32 v122, 1.0, v122
	v_add_f32_e32 v123, 1.0, v123
	v_rcp_f32_e32 v122, v122
	v_rcp_f32_e32 v123, v123
	v_mul_f32_e32 v122, 0xbf60028b, v122
	v_mul_f32_e32 v123, 0xbf60028b, v123
	v_exp_f32_e32 v122, v122
	v_exp_f32_e32 v123, v123
	s_nop 0
	v_lshl_add_u64 v[130:131], v[130:131], 2, s[46:47]
	global_store_dwordx4 v[130:131], v[124:127], off
	global_store_dwordx4 v[130:131], v[120:123], off offset:16

;     __device__ __forceinline__ void operator()(const f32x4 (&acc)[2][2][4][2], const pg8::Unit& u, int wr, int wc, int fr, int fq) const {
;     ...
;                     if (kind == 0) {
; #pragma unroll
;                         for (int i = 0; i < 4; ++i) {
;                             { const float z = -v0[i]; const float sp_ = fmaxf(z, 0.f) + __logf(1.f + __expf(-fabsf(z))); v0[i] = __expf(-__expf(-sp_ - 0.5f)); }
;                             { const float z = -v1[i]; const float sp_ = fmaxf(z, 0.f) + __logf(1.f + __expf(-fabsf(z))); v1[i] = __expf(-__expf(-sp_ - 0.5f)); }
;                         }
;                         *(f32x4*)(DEC + off) = v0; *(f32x4*)(DEC + off + 4) = v1;
.LBB0_465:
	s_and_b64 vcc, exec, s[0:1]
	s_cbranch_vccz .LBB0_467
	v_mul_f32_e32 v116, 0xbfb8aa3b, v116
	v_mul_f32_e32 v117, 0xbfb8aa3b, v117
	v_exp_f32_e32 v116, v116
	v_exp_f32_e32 v117, v117
	v_add_f32_e32 v116, 1.0, v116
	v_add_f32_e32 v117, 1.0, v117
	v_rcp_f32_e32 v116, v116
	v_rcp_f32_e32 v117, v117
	v_mul_f32_e32 v116, 0xbf60028b, v116
	v_mul_f32_e32 v117, 0xbf60028b, v117
	v_exp_f32_e32 v116, v116
	v_exp_f32_e32 v117, v117
	v_mul_f32_e32 v118, 0xbfb8aa3b, v118
	v_mul_f32_e32 v119, 0xbfb8aa3b, v119
	v_exp_f32_e32 v118, v118
	v_exp_f32_e32 v119, v119
	v_add_f32_e32 v118, 1.0, v118
	v_add_f32_e32 v119, 1.0, v119
	v_rcp_f32_e32 v118, v118
	v_rcp_f32_e32 v119, v119
	v_mul_f32_e32 v118, 0xbf60028b, v118
	v_mul_f32_e32 v119, 0xbf60028b, v119
	v_exp_f32_e32 v118, v118
	v_exp_f32_e32 v119, v119
	v_mul_f32_e32 v112, 0xbfb8aa3b, v112
	v_mul_f32_e32 v113, 0xbfb8aa3b, v113
	v_exp_f32_e32 v112, v112
	v_exp_f32_e32 v113, v113
	v_add_f32_e32 v112, 1.0, v112
	v_add_f32_e32 v113, 1.0, v113
	v_rcp_f32_e32 v112, v112
	v_rcp_f32_e32 v113, v113
	v_mul_f32_e32 v112, 0xbf60028b, v112
	v_mul_f32_e32 v113, 0xbf60028b, v113
	v_exp_f32_e32 v112, v112
	v_exp_f32_e32 v113, v113
	v_mul_f32_e32 v114, 0xbfb8aa3b, v114
	v_mul_f32_e32 v115, 0xbfb8aa3b, v115
	v_exp_f32_e32 v114, v114
	v_exp_f32_e32 v115, v115
	v_add_f32_e32 v114, 1.0, v114
	v_add_f32_e32 v115, 1.0, v115
	v_rcp_f32_e32 v114, v114
	v_rcp_f32_e32 v115, v115
	v_mul_f32_e32 v114, 0xbf60028b, v114
	v_mul_f32_e32 v115, 0xbf60028b, v115
	v_exp_f32_e32 v114, v114
	v_exp_f32_e32 v115, v115
	s_nop 0
	v_lshl_add_u64 v[122:123], v[122:123], 2, s[46:47]
	global_store_dwordx4 v[122:123], v[116:119], off
	global_store_dwordx4 v[122:123], v[112:115], off offset:16

;     __device__ __forceinline__ void operator()(const f32x4 (&acc)[2][2][4][2], const pg8::Unit& u, int wr, int wc, int fr, int fq) const {
;     ...
;                     if (kind == 0) {
; #pragma unroll
;                         for (int i = 0; i < 4; ++i) {
;                             { const float z = -v0[i]; const float sp_ = fmaxf(z, 0.f) + __logf(1.f + __expf(-fabsf(z))); v0[i] = __expf(-__expf(-sp_ - 0.5f)); }
;                             { const float z = -v1[i]; const float sp_ = fmaxf(z, 0.f) + __logf(1.f + __expf(-fabsf(z))); v1[i] = __expf(-__expf(-sp_ - 0.5f)); }
;                         }
;                         *(f32x4*)(DEC + off) = v0; *(f32x4*)(DEC + off + 4) = v1;
.LBB0_471:
	s_and_b64 vcc, exec, s[0:1]
	s_cbranch_vccz .LBB0_473
	v_mul_f32_e32 v108, 0xbfb8aa3b, v108
	v_mul_f32_e32 v109, 0xbfb8aa3b, v109
	v_exp_f32_e32 v108, v108
	v_exp_f32_e32 v109, v109
	v_add_f32_e32 v108, 1.0, v108
	v_add_f32_e32 v109, 1.0, v109
	v_rcp_f32_e32 v108, v108
	v_rcp_f32_e32 v109, v109
	v_mul_f32_e32 v108, 0xbf60028b, v108
	v_mul_f32_e32 v109, 0xbf60028b, v109
	v_exp_f32_e32 v108, v108
	v_exp_f32_e32 v109, v109
	v_mul_f32_e32 v110, 0xbfb8aa3b, v110
	v_mul_f32_e32 v111, 0xbfb8aa3b, v111
	v_exp_f32_e32 v110, v110
	v_exp_f32_e32 v111, v111
	v_add_f32_e32 v110, 1.0, v110
	v_add_f32_e32 v111, 1.0, v111
	v_rcp_f32_e32 v110, v110
	v_rcp_f32_e32 v111, v111
	v_mul_f32_e32 v110, 0xbf60028b, v110
	v_mul_f32_e32 v111, 0xbf60028b, v111
	v_exp_f32_e32 v110, v110
	v_exp_f32_e32 v111, v111
	v_mul_f32_e32 v104, 0xbfb8aa3b, v104
	v_mul_f32_e32 v105, 0xbfb8aa3b, v105
	v_exp_f32_e32 v104, v104
	v_exp_f32_e32 v105, v105
	v_add_f32_e32 v104, 1.0, v104
	v_add_f32_e32 v105, 1.0, v105
	v_rcp_f32_e32 v104, v104
	v_rcp_f32_e32 v105, v105
	v_mul_f32_e32 v104, 0xbf60028b, v104
	v_mul_f32_e32 v105, 0xbf60028b, v105
	v_exp_f32_e32 v104, v104
	v_exp_f32_e32 v105, v105
	v_mul_f32_e32 v106, 0xbfb8aa3b, v106
	v_mul_f32_e32 v107, 0xbfb8aa3b, v107
	v_exp_f32_e32 v106, v106
	v_exp_f32_e32 v107, v107
	v_add_f32_e32 v106, 1.0, v106
	v_add_f32_e32 v107, 1.0, v107
	v_rcp_f32_e32 v106, v106
	v_rcp_f32_e32 v107, v107
	v_mul_f32_e32 v106, 0xbf60028b, v106
	v_mul_f32_e32 v107, 0xbf60028b, v107
	v_exp_f32_e32 v106, v106
	v_exp_f32_e32 v107, v107
	s_nop 0
	v_lshl_add_u64 v[114:115], v[114:115], 2, s[46:47]
	global_store_dwordx4 v[114:115], v[108:111], off
	global_store_dwordx4 v[114:115], v[104:107], off offset:16

;     __device__ __forceinline__ void operator()(const f32x4 (&acc)[2][2][4][2], const pg8::Unit& u, int wr, int wc, int fr, int fq) const {
;     ...
;                     if (kind == 0) {
; #pragma unroll
;                         for (int i = 0; i < 4; ++i) {
;                             { const float z = -v0[i]; const float sp_ = fmaxf(z, 0.f) + __logf(1.f + __expf(-fabsf(z))); v0[i] = __expf(-__expf(-sp_ - 0.5f)); }
;                             { const float z = -v1[i]; const float sp_ = fmaxf(z, 0.f) + __logf(1.f + __expf(-fabsf(z))); v1[i] = __expf(-__expf(-sp_ - 0.5f)); }
;                         }
;                         *(f32x4*)(DEC + off) = v0; *(f32x4*)(DEC + off + 4) = v1;
.LBB0_477:
	s_and_b64 vcc, exec, s[0:1]
	s_cbranch_vccz .LBB0_479
	v_mul_f32_e32 v100, 0xbfb8aa3b, v100
	v_mul_f32_e32 v101, 0xbfb8aa3b, v101
	v_exp_f32_e32 v100, v100
	v_exp_f32_e32 v101, v101
	v_add_f32_e32 v100, 1.0, v100
	v_add_f32_e32 v101, 1.0, v101
	v_rcp_f32_e32 v100, v100
	v_rcp_f32_e32 v101, v101
	v_mul_f32_e32 v100, 0xbf60028b, v100
	v_mul_f32_e32 v101, 0xbf60028b, v101
	v_exp_f32_e32 v100, v100
	v_exp_f32_e32 v101, v101
	v_mul_f32_e32 v102, 0xbfb8aa3b, v102
	v_mul_f32_e32 v103, 0xbfb8aa3b, v103
	v_exp_f32_e32 v102, v102
	v_exp_f32_e32 v103, v103
	v_add_f32_e32 v102, 1.0, v102
	v_add_f32_e32 v103, 1.0, v103
	v_rcp_f32_e32 v102, v102
	v_rcp_f32_e32 v103, v103
	v_mul_f32_e32 v102, 0xbf60028b, v102
	v_mul_f32_e32 v103, 0xbf60028b, v103
	v_exp_f32_e32 v102, v102
	v_exp_f32_e32 v103, v103
	v_mul_f32_e32 v96, 0xbfb8aa3b, v96
	v_mul_f32_e32 v97, 0xbfb8aa3b, v97
	v_exp_f32_e32 v96, v96
	v_exp_f32_e32 v97, v97
	v_add_f32_e32 v96, 1.0, v96
	v_add_f32_e32 v97, 1.0, v97
	v_rcp_f32_e32 v96, v96
	v_rcp_f32_e32 v97, v97
	v_mul_f32_e32 v96, 0xbf60028b, v96
	v_mul_f32_e32 v97, 0xbf60028b, v97
	v_exp_f32_e32 v96, v96
	v_exp_f32_e32 v97, v97
	v_mul_f32_e32 v98, 0xbfb8aa3b, v98
	v_mul_f32_e32 v99, 0xbfb8aa3b, v99
	v_exp_f32_e32 v98, v98
	v_exp_f32_e32 v99, v99
	v_add_f32_e32 v98, 1.0, v98
	v_add_f32_e32 v99, 1.0, v99
	v_rcp_f32_e32 v98, v98
	v_rcp_f32_e32 v99, v99
	v_mul_f32_e32 v98, 0xbf60028b, v98
	v_mul_f32_e32 v99, 0xbf60028b, v99
	v_exp_f32_e32 v98, v98
	v_exp_f32_e32 v99, v99
	s_nop 0
	v_lshl_add_u64 v[106:107], v[106:107], 2, s[46:47]
	global_store_dwordx4 v[106:107], v[100:103], off
	global_store_dwordx4 v[106:107], v[96:99], off offset:16

;     __device__ __forceinline__ void operator()(const f32x4 (&acc)[2][2][4][2], const pg8::Unit& u, int wr, int wc, int fr, int fq) const {
;     ...
;                     if (kind == 0) {
; #pragma unroll
;                         for (int i = 0; i < 4; ++i) {
;                             { const float z = -v0[i]; const float sp_ = fmaxf(z, 0.f) + __logf(1.f + __expf(-fabsf(z))); v0[i] = __expf(-__expf(-sp_ - 0.5f)); }
;                             { const float z = -v1[i]; const float sp_ = fmaxf(z, 0.f) + __logf(1.f + __expf(-fabsf(z))); v1[i] = __expf(-__expf(-sp_ - 0.5f)); }
;                         }
;                         *(f32x4*)(DEC + off) = v0; *(f32x4*)(DEC + off + 4) = v1;
.LBB0_483:
	s_and_b64 vcc, exec, s[0:1]
	s_cbranch_vccz .LBB0_485
	v_mul_f32_e32 v84, 0xbfb8aa3b, v84
	v_mul_f32_e32 v85, 0xbfb8aa3b, v85
	v_exp_f32_e32 v84, v84
	v_exp_f32_e32 v85, v85
	v_add_f32_e32 v84, 1.0, v84
	v_add_f32_e32 v85, 1.0, v85
	v_rcp_f32_e32 v84, v84
	v_rcp_f32_e32 v85, v85
	v_mul_f32_e32 v84, 0xbf60028b, v84
	v_mul_f32_e32 v85, 0xbf60028b, v85
	v_exp_f32_e32 v84, v84
	v_exp_f32_e32 v85, v85
	v_mul_f32_e32 v86, 0xbfb8aa3b, v86
	v_mul_f32_e32 v87, 0xbfb8aa3b, v87
	v_exp_f32_e32 v86, v86
	v_exp_f32_e32 v87, v87
	v_add_f32_e32 v86, 1.0, v86
	v_add_f32_e32 v87, 1.0, v87
	v_rcp_f32_e32 v86, v86
	v_rcp_f32_e32 v87, v87
	v_mul_f32_e32 v86, 0xbf60028b, v86
	v_mul_f32_e32 v87, 0xbf60028b, v87
	v_exp_f32_e32 v86, v86
	v_exp_f32_e32 v87, v87
	v_mul_f32_e32 v80, 0xbfb8aa3b, v80
	v_mul_f32_e32 v81, 0xbfb8aa3b, v81
	v_exp_f32_e32 v80, v80
	v_exp_f32_e32 v81, v81
	v_add_f32_e32 v80, 1.0, v80
	v_add_f32_e32 v81, 1.0, v81
	v_rcp_f32_e32 v80, v80
	v_rcp_f32_e32 v81, v81
	v_mul_f32_e32 v80, 0xbf60028b, v80
	v_mul_f32_e32 v81, 0xbf60028b, v81
	v_exp_f32_e32 v80, v80
	v_exp_f32_e32 v81, v81
	v_mul_f32_e32 v82, 0xbfb8aa3b, v82
	v_mul_f32_e32 v83, 0xbfb8aa3b, v83
	v_exp_f32_e32 v82, v82
	v_exp_f32_e32 v83, v83
	v_add_f32_e32 v82, 1.0, v82
	v_add_f32_e32 v83, 1.0, v83
	v_rcp_f32_e32 v82, v82
	v_rcp_f32_e32 v83, v83
	v_mul_f32_e32 v82, 0xbf60028b, v82
	v_mul_f32_e32 v83, 0xbf60028b, v83
	v_exp_f32_e32 v82, v82
	v_exp_f32_e32 v83, v83
	s_nop 0
	v_lshl_add_u64 v[98:99], v[98:99], 2, s[46:47]
	global_store_dwordx4 v[98:99], v[84:87], off
	global_store_dwordx4 v[98:99], v[80:83], off offset:16

;     __device__ __forceinline__ void operator()(const f32x4 (&acc)[2][2][4][2], const pg8::Unit& u, int wr, int wc, int fr, int fq) const {
;     ...
;                     if (kind == 0) {
; #pragma unroll
;                         for (int i = 0; i < 4; ++i) {
;                             { const float z = -v0[i]; const float sp_ = fmaxf(z, 0.f) + __logf(1.f + __expf(-fabsf(z))); v0[i] = __expf(-__expf(-sp_ - 0.5f)); }
;                             { const float z = -v1[i]; const float sp_ = fmaxf(z, 0.f) + __logf(1.f + __expf(-fabsf(z))); v1[i] = __expf(-__expf(-sp_ - 0.5f)); }
;                         }
;                         *(f32x4*)(DEC + off) = v0; *(f32x4*)(DEC + off + 4) = v1;
.LBB0_489:
	s_and_b64 vcc, exec, s[0:1]
	s_cbranch_vccz .LBB0_491
	v_mul_f32_e32 v76, 0xbfb8aa3b, v76
	v_mul_f32_e32 v77, 0xbfb8aa3b, v77
	v_exp_f32_e32 v76, v76
	v_exp_f32_e32 v77, v77
	v_add_f32_e32 v76, 1.0, v76
	v_add_f32_e32 v77, 1.0, v77
	v_rcp_f32_e32 v76, v76
	v_rcp_f32_e32 v77, v77
	v_mul_f32_e32 v76, 0xbf60028b, v76
	v_mul_f32_e32 v77, 0xbf60028b, v77
	v_exp_f32_e32 v76, v76
	v_exp_f32_e32 v77, v77
	v_mul_f32_e32 v78, 0xbfb8aa3b, v78
	v_mul_f32_e32 v79, 0xbfb8aa3b, v79
	v_exp_f32_e32 v78, v78
	v_exp_f32_e32 v79, v79
	v_add_f32_e32 v78, 1.0, v78
	v_add_f32_e32 v79, 1.0, v79
	v_rcp_f32_e32 v78, v78
	v_rcp_f32_e32 v79, v79
	v_mul_f32_e32 v78, 0xbf60028b, v78
	v_mul_f32_e32 v79, 0xbf60028b, v79
	v_exp_f32_e32 v78, v78
	v_exp_f32_e32 v79, v79
	v_mul_f32_e32 v72, 0xbfb8aa3b, v72
	v_mul_f32_e32 v73, 0xbfb8aa3b, v73
	v_exp_f32_e32 v72, v72
	v_exp_f32_e32 v73, v73
	v_add_f32_e32 v72, 1.0, v72
	v_add_f32_e32 v73, 1.0, v73
	v_rcp_f32_e32 v72, v72
	v_rcp_f32_e32 v73, v73
	v_mul_f32_e32 v72, 0xbf60028b, v72
	v_mul_f32_e32 v73, 0xbf60028b, v73
	v_exp_f32_e32 v72, v72
	v_exp_f32_e32 v73, v73
	v_mul_f32_e32 v74, 0xbfb8aa3b, v74
	v_mul_f32_e32 v75, 0xbfb8aa3b, v75
	v_exp_f32_e32 v74, v74
	v_exp_f32_e32 v75, v75
	v_add_f32_e32 v74, 1.0, v74
	v_add_f32_e32 v75, 1.0, v75
	v_rcp_f32_e32 v74, v74
	v_rcp_f32_e32 v75, v75
	v_mul_f32_e32 v74, 0xbf60028b, v74
	v_mul_f32_e32 v75, 0xbf60028b, v75
	v_exp_f32_e32 v74, v74
	v_exp_f32_e32 v75, v75
	s_nop 0
	v_lshl_add_u64 v[82:83], v[82:83], 2, s[46:47]
	global_store_dwordx4 v[82:83], v[76:79], off
	global_store_dwordx4 v[82:83], v[72:75], off offset:16

;     __device__ __forceinline__ void operator()(const f32x4 (&acc)[2][2][4][2], const pg8::Unit& u, int wr, int wc, int fr, int fq) const {
;     ...
;                     if (kind == 0) {
; #pragma unroll
;                         for (int i = 0; i < 4; ++i) {
;                             { const float z = -v0[i]; const float sp_ = fmaxf(z, 0.f) + __logf(1.f + __expf(-fabsf(z))); v0[i] = __expf(-__expf(-sp_ - 0.5f)); }
;                             { const float z = -v1[i]; const float sp_ = fmaxf(z, 0.f) + __logf(1.f + __expf(-fabsf(z))); v1[i] = __expf(-__expf(-sp_ - 0.5f)); }
;                         }
;                         *(f32x4*)(DEC + off) = v0; *(f32x4*)(DEC + off + 4) = v1;
.LBB0_495:
	s_waitcnt lgkmcnt(0)
	s_mov_b64 s[0:1], s[80:81]
	s_cbranch_execz .LBB0_497
	v_mul_f32_e32 v68, 0xbfb8aa3b, v68
	v_mul_f32_e32 v69, 0xbfb8aa3b, v69
	v_exp_f32_e32 v68, v68
	v_exp_f32_e32 v69, v69
	v_add_f32_e32 v68, 1.0, v68
	v_add_f32_e32 v69, 1.0, v69
	v_rcp_f32_e32 v68, v68
	v_rcp_f32_e32 v69, v69
	v_mul_f32_e32 v68, 0xbf60028b, v68
	v_mul_f32_e32 v69, 0xbf60028b, v69
	v_exp_f32_e32 v68, v68
	v_exp_f32_e32 v69, v69
	v_mul_f32_e32 v70, 0xbfb8aa3b, v70
	v_mul_f32_e32 v71, 0xbfb8aa3b, v71
	v_exp_f32_e32 v70, v70
	v_exp_f32_e32 v71, v71
	v_add_f32_e32 v70, 1.0, v70
	v_add_f32_e32 v71, 1.0, v71
	v_rcp_f32_e32 v70, v70
	v_rcp_f32_e32 v71, v71
	v_mul_f32_e32 v70, 0xbf60028b, v70
	v_mul_f32_e32 v71, 0xbf60028b, v71
	v_exp_f32_e32 v70, v70
	v_exp_f32_e32 v71, v71
	v_mul_f32_e32 v64, 0xbfb8aa3b, v64
	v_mul_f32_e32 v65, 0xbfb8aa3b, v65
	v_exp_f32_e32 v64, v64
	v_exp_f32_e32 v65, v65
	v_add_f32_e32 v64, 1.0, v64
	v_add_f32_e32 v65, 1.0, v65
	v_rcp_f32_e32 v64, v64
	v_rcp_f32_e32 v65, v65
	v_mul_f32_e32 v64, 0xbf60028b, v64
	v_mul_f32_e32 v65, 0xbf60028b, v65
	v_exp_f32_e32 v64, v64
	v_exp_f32_e32 v65, v65
	v_mul_f32_e32 v66, 0xbfb8aa3b, v66
	v_mul_f32_e32 v67, 0xbfb8aa3b, v67
	v_exp_f32_e32 v66, v66
	v_exp_f32_e32 v67, v67
	v_add_f32_e32 v66, 1.0, v66
	v_add_f32_e32 v67, 1.0, v67
	v_rcp_f32_e32 v66, v66
	v_rcp_f32_e32 v67, v67
	v_mul_f32_e32 v66, 0xbf60028b, v66
	v_mul_f32_e32 v67, 0xbf60028b, v67
	v_exp_f32_e32 v66, v66
	v_exp_f32_e32 v67, v67
	s_nop 0
	v_lshl_add_u64 v[74:75], v[74:75], 2, s[46:47]
	global_store_dwordx4 v[74:75], v[68:71], off
	global_store_dwordx4 v[74:75], v[64:67], off offset:16

;     __device__ __forceinline__ void operator()(const f32x4 (&acc)[2][2][4][2], const pg8::Unit& u, int wr, int wc, int fr, int fq) const {
;     ...
;                     if (kind == 0) {
; #pragma unroll
;                         for (int i = 0; i < 4; ++i) {
;                             { const float z = -v0[i]; const float sp_ = fmaxf(z, 0.f) + __logf(1.f + __expf(-fabsf(z))); v0[i] = __expf(-__expf(-sp_ - 0.5f)); }
;                             { const float z = -v1[i]; const float sp_ = fmaxf(z, 0.f) + __logf(1.f + __expf(-fabsf(z))); v1[i] = __expf(-__expf(-sp_ - 0.5f)); }
;                         }
;                         *(f32x4*)(DEC + off) = v0; *(f32x4*)(DEC + off + 4) = v1;
.LBB0_503:
	v_or_b32_e32 v74, 0x80, v152
	s_and_b64 vcc, exec, s[0:1]
	s_cbranch_vccz .LBB0_505
	v_mul_f32_e32 v60, 0xbfb8aa3b, v60
	v_mul_f32_e32 v61, 0xbfb8aa3b, v61
	v_exp_f32_e32 v60, v60
	v_exp_f32_e32 v61, v61
	v_add_f32_e32 v60, 1.0, v60
	v_add_f32_e32 v61, 1.0, v61
	v_rcp_f32_e32 v60, v60
	v_rcp_f32_e32 v61, v61
	v_mul_f32_e32 v60, 0xbf60028b, v60
	v_mul_f32_e32 v61, 0xbf60028b, v61
	v_exp_f32_e32 v60, v60
	v_exp_f32_e32 v61, v61
	v_mul_f32_e32 v62, 0xbfb8aa3b, v62
	v_mul_f32_e32 v63, 0xbfb8aa3b, v63
	v_exp_f32_e32 v62, v62
	v_exp_f32_e32 v63, v63
	v_add_f32_e32 v62, 1.0, v62
	v_add_f32_e32 v63, 1.0, v63
	v_rcp_f32_e32 v62, v62
	v_rcp_f32_e32 v63, v63
	v_mul_f32_e32 v62, 0xbf60028b, v62
	v_mul_f32_e32 v63, 0xbf60028b, v63
	v_exp_f32_e32 v62, v62
	v_exp_f32_e32 v63, v63
	v_mul_f32_e32 v56, 0xbfb8aa3b, v56
	v_mul_f32_e32 v57, 0xbfb8aa3b, v57
	v_exp_f32_e32 v56, v56
	v_exp_f32_e32 v57, v57
	v_add_f32_e32 v56, 1.0, v56
	v_add_f32_e32 v57, 1.0, v57
	v_rcp_f32_e32 v56, v56
	v_rcp_f32_e32 v57, v57
	v_mul_f32_e32 v56, 0xbf60028b, v56
	v_mul_f32_e32 v57, 0xbf60028b, v57
	v_exp_f32_e32 v56, v56
	v_exp_f32_e32 v57, v57
	v_mul_f32_e32 v58, 0xbfb8aa3b, v58
	v_mul_f32_e32 v59, 0xbfb8aa3b, v59
	v_exp_f32_e32 v58, v58
	v_exp_f32_e32 v59, v59
	v_add_f32_e32 v58, 1.0, v58
	v_add_f32_e32 v59, 1.0, v59
	v_rcp_f32_e32 v58, v58
	v_rcp_f32_e32 v59, v59
	v_mul_f32_e32 v58, 0xbf60028b, v58
	v_mul_f32_e32 v59, 0xbf60028b, v59
	v_exp_f32_e32 v58, v58
	v_exp_f32_e32 v59, v59
	s_nop 0
	v_or_b32_e32 v148, v148, v74
	v_lshl_add_u64 v[76:77], v[148:149], 2, s[46:47]
	global_store_dwordx4 v[76:77], v[60:63], off
	global_store_dwordx4 v[76:77], v[56:59], off offset:16

;     __device__ __forceinline__ void operator()(const f32x4 (&acc)[2][2][4][2], const pg8::Unit& u, int wr, int wc, int fr, int fq) const {
;     ...
;                     if (kind == 0) {
; #pragma unroll
;                         for (int i = 0; i < 4; ++i) {
;                             { const float z = -v0[i]; const float sp_ = fmaxf(z, 0.f) + __logf(1.f + __expf(-fabsf(z))); v0[i] = __expf(-__expf(-sp_ - 0.5f)); }
;                             { const float z = -v1[i]; const float sp_ = fmaxf(z, 0.f) + __logf(1.f + __expf(-fabsf(z))); v1[i] = __expf(-__expf(-sp_ - 0.5f)); }
;                         }
;                         *(f32x4*)(DEC + off) = v0; *(f32x4*)(DEC + off + 4) = v1;
.LBB0_509:
	s_and_b64 vcc, exec, s[0:1]
	s_cbranch_vccz .LBB0_511
	v_mul_f32_e32 v52, 0xbfb8aa3b, v52
	v_mul_f32_e32 v53, 0xbfb8aa3b, v53
	v_exp_f32_e32 v52, v52
	v_exp_f32_e32 v53, v53
	v_add_f32_e32 v52, 1.0, v52
	v_add_f32_e32 v53, 1.0, v53
	v_rcp_f32_e32 v52, v52
	v_rcp_f32_e32 v53, v53
	v_mul_f32_e32 v52, 0xbf60028b, v52
	v_mul_f32_e32 v53, 0xbf60028b, v53
	v_exp_f32_e32 v52, v52
	v_exp_f32_e32 v53, v53
	v_mul_f32_e32 v54, 0xbfb8aa3b, v54
	v_mul_f32_e32 v55, 0xbfb8aa3b, v55
	v_exp_f32_e32 v54, v54
	v_exp_f32_e32 v55, v55
	v_add_f32_e32 v54, 1.0, v54
	v_add_f32_e32 v55, 1.0, v55
	v_rcp_f32_e32 v54, v54
	v_rcp_f32_e32 v55, v55
	v_mul_f32_e32 v54, 0xbf60028b, v54
	v_mul_f32_e32 v55, 0xbf60028b, v55
	v_exp_f32_e32 v54, v54
	v_exp_f32_e32 v55, v55
	v_mul_f32_e32 v48, 0xbfb8aa3b, v48
	v_mul_f32_e32 v49, 0xbfb8aa3b, v49
	v_exp_f32_e32 v48, v48
	v_exp_f32_e32 v49, v49
	v_add_f32_e32 v48, 1.0, v48
	v_add_f32_e32 v49, 1.0, v49
	v_rcp_f32_e32 v48, v48
	v_rcp_f32_e32 v49, v49
	v_mul_f32_e32 v48, 0xbf60028b, v48
	v_mul_f32_e32 v49, 0xbf60028b, v49
	v_exp_f32_e32 v48, v48
	v_exp_f32_e32 v49, v49
	v_mul_f32_e32 v50, 0xbfb8aa3b, v50
	v_mul_f32_e32 v51, 0xbfb8aa3b, v51
	v_exp_f32_e32 v50, v50
	v_exp_f32_e32 v51, v51
	v_add_f32_e32 v50, 1.0, v50
	v_add_f32_e32 v51, 1.0, v51
	v_rcp_f32_e32 v50, v50
	v_rcp_f32_e32 v51, v51
	v_mul_f32_e32 v50, 0xbf60028b, v50
	v_mul_f32_e32 v51, 0xbf60028b, v51
	v_exp_f32_e32 v50, v50
	v_exp_f32_e32 v51, v51
	s_nop 0
	v_or_b32_e32 v128, v128, v74
	v_lshl_add_u64 v[56:57], v[128:129], 2, s[46:47]
	global_store_dwordx4 v[56:57], v[52:55], off
	global_store_dwordx4 v[56:57], v[48:51], off offset:16

;     __device__ __forceinline__ void operator()(const f32x4 (&acc)[2][2][4][2], const pg8::Unit& u, int wr, int wc, int fr, int fq) const {
;     ...
;                     if (kind == 0) {
; #pragma unroll
;                         for (int i = 0; i < 4; ++i) {
;                             { const float z = -v0[i]; const float sp_ = fmaxf(z, 0.f) + __logf(1.f + __expf(-fabsf(z))); v0[i] = __expf(-__expf(-sp_ - 0.5f)); }
;                             { const float z = -v1[i]; const float sp_ = fmaxf(z, 0.f) + __logf(1.f + __expf(-fabsf(z))); v1[i] = __expf(-__expf(-sp_ - 0.5f)); }
;                         }
;                         *(f32x4*)(DEC + off) = v0; *(f32x4*)(DEC + off + 4) = v1;
.LBB0_515:
	s_and_b64 vcc, exec, s[0:1]
	s_cbranch_vccz .LBB0_517
	v_mul_f32_e32 v44, 0xbfb8aa3b, v44
	v_mul_f32_e32 v45, 0xbfb8aa3b, v45
	v_exp_f32_e32 v44, v44
	v_exp_f32_e32 v45, v45
	v_add_f32_e32 v44, 1.0, v44
	v_add_f32_e32 v45, 1.0, v45
	v_rcp_f32_e32 v44, v44
	v_rcp_f32_e32 v45, v45
	v_mul_f32_e32 v44, 0xbf60028b, v44
	v_mul_f32_e32 v45, 0xbf60028b, v45
	v_exp_f32_e32 v44, v44
	v_exp_f32_e32 v45, v45
	v_mul_f32_e32 v46, 0xbfb8aa3b, v46
	v_mul_f32_e32 v47, 0xbfb8aa3b, v47
	v_exp_f32_e32 v46, v46
	v_exp_f32_e32 v47, v47
	v_add_f32_e32 v46, 1.0, v46
	v_add_f32_e32 v47, 1.0, v47
	v_rcp_f32_e32 v46, v46
	v_rcp_f32_e32 v47, v47
	v_mul_f32_e32 v46, 0xbf60028b, v46
	v_mul_f32_e32 v47, 0xbf60028b, v47
	v_exp_f32_e32 v46, v46
	v_exp_f32_e32 v47, v47
	v_mul_f32_e32 v40, 0xbfb8aa3b, v40
	v_mul_f32_e32 v41, 0xbfb8aa3b, v41
	v_exp_f32_e32 v40, v40
	v_exp_f32_e32 v41, v41
	v_add_f32_e32 v40, 1.0, v40
	v_add_f32_e32 v41, 1.0, v41
	v_rcp_f32_e32 v40, v40
	v_rcp_f32_e32 v41, v41
	v_mul_f32_e32 v40, 0xbf60028b, v40
	v_mul_f32_e32 v41, 0xbf60028b, v41
	v_exp_f32_e32 v40, v40
	v_exp_f32_e32 v41, v41
	v_mul_f32_e32 v42, 0xbfb8aa3b, v42
	v_mul_f32_e32 v43, 0xbfb8aa3b, v43
	v_exp_f32_e32 v42, v42
	v_exp_f32_e32 v43, v43
	v_add_f32_e32 v42, 1.0, v42
	v_add_f32_e32 v43, 1.0, v43
	v_rcp_f32_e32 v42, v42
	v_rcp_f32_e32 v43, v43
	v_mul_f32_e32 v42, 0xbf60028b, v42
	v_mul_f32_e32 v43, 0xbf60028b, v43
	v_exp_f32_e32 v42, v42
	v_exp_f32_e32 v43, v43
	s_nop 0
	v_or_b32_e32 v120, v120, v74
	v_lshl_add_u64 v[48:49], v[120:121], 2, s[46:47]
	global_store_dwordx4 v[48:49], v[44:47], off
	global_store_dwordx4 v[48:49], v[40:43], off offset:16

;     __device__ __forceinline__ void operator()(const f32x4 (&acc)[2][2][4][2], const pg8::Unit& u, int wr, int wc, int fr, int fq) const {
;     ...
;                     if (kind == 0) {
; #pragma unroll
;                         for (int i = 0; i < 4; ++i) {
;                             { const float z = -v0[i]; const float sp_ = fmaxf(z, 0.f) + __logf(1.f + __expf(-fabsf(z))); v0[i] = __expf(-__expf(-sp_ - 0.5f)); }
;                             { const float z = -v1[i]; const float sp_ = fmaxf(z, 0.f) + __logf(1.f + __expf(-fabsf(z))); v1[i] = __expf(-__expf(-sp_ - 0.5f)); }
;                         }
;                         *(f32x4*)(DEC + off) = v0; *(f32x4*)(DEC + off + 4) = v1;
.LBB0_521:
	s_and_b64 vcc, exec, s[0:1]
	s_cbranch_vccz .LBB0_523
	v_mul_f32_e32 v36, 0xbfb8aa3b, v36
	v_mul_f32_e32 v37, 0xbfb8aa3b, v37
	v_exp_f32_e32 v36, v36
	v_exp_f32_e32 v37, v37
	v_add_f32_e32 v36, 1.0, v36
	v_add_f32_e32 v37, 1.0, v37
	v_rcp_f32_e32 v36, v36
	v_rcp_f32_e32 v37, v37
	v_mul_f32_e32 v36, 0xbf60028b, v36
	v_mul_f32_e32 v37, 0xbf60028b, v37
	v_exp_f32_e32 v36, v36
	v_exp_f32_e32 v37, v37
	v_mul_f32_e32 v38, 0xbfb8aa3b, v38
	v_mul_f32_e32 v39, 0xbfb8aa3b, v39
	v_exp_f32_e32 v38, v38
	v_exp_f32_e32 v39, v39
	v_add_f32_e32 v38, 1.0, v38
	v_add_f32_e32 v39, 1.0, v39
	v_rcp_f32_e32 v38, v38
	v_rcp_f32_e32 v39, v39
	v_mul_f32_e32 v38, 0xbf60028b, v38
	v_mul_f32_e32 v39, 0xbf60028b, v39
	v_exp_f32_e32 v38, v38
	v_exp_f32_e32 v39, v39
	v_mul_f32_e32 v32, 0xbfb8aa3b, v32
	v_mul_f32_e32 v33, 0xbfb8aa3b, v33
	v_exp_f32_e32 v32, v32
	v_exp_f32_e32 v33, v33
	v_add_f32_e32 v32, 1.0, v32
	v_add_f32_e32 v33, 1.0, v33
	v_rcp_f32_e32 v32, v32
	v_rcp_f32_e32 v33, v33
	v_mul_f32_e32 v32, 0xbf60028b, v32
	v_mul_f32_e32 v33, 0xbf60028b, v33
	v_exp_f32_e32 v32, v32
	v_exp_f32_e32 v33, v33
	v_mul_f32_e32 v34, 0xbfb8aa3b, v34
	v_mul_f32_e32 v35, 0xbfb8aa3b, v35
	v_exp_f32_e32 v34, v34
	v_exp_f32_e32 v35, v35
	v_add_f32_e32 v34, 1.0, v34
	v_add_f32_e32 v35, 1.0, v35
	v_rcp_f32_e32 v34, v34
	v_rcp_f32_e32 v35, v35
	v_mul_f32_e32 v34, 0xbf60028b, v34
	v_mul_f32_e32 v35, 0xbf60028b, v35
	v_exp_f32_e32 v34, v34
	v_exp_f32_e32 v35, v35
	s_nop 0
	v_or_b32_e32 v112, v112, v74
	v_lshl_add_u64 v[40:41], v[112:113], 2, s[46:47]
	global_store_dwordx4 v[40:41], v[36:39], off
	global_store_dwordx4 v[40:41], v[32:35], off offset:16

;     __device__ __forceinline__ void operator()(const f32x4 (&acc)[2][2][4][2], const pg8::Unit& u, int wr, int wc, int fr, int fq) const {
;     ...
;                     if (kind == 0) {
; #pragma unroll
;                         for (int i = 0; i < 4; ++i) {
;                             { const float z = -v0[i]; const float sp_ = fmaxf(z, 0.f) + __logf(1.f + __expf(-fabsf(z))); v0[i] = __expf(-__expf(-sp_ - 0.5f)); }
;                             { const float z = -v1[i]; const float sp_ = fmaxf(z, 0.f) + __logf(1.f + __expf(-fabsf(z))); v1[i] = __expf(-__expf(-sp_ - 0.5f)); }
;                         }
;                         *(f32x4*)(DEC + off) = v0; *(f32x4*)(DEC + off + 4) = v1;
.LBB0_527:
	s_and_b64 vcc, exec, s[0:1]
	s_cbranch_vccz .LBB0_529
	v_mul_f32_e32 v28, 0xbfb8aa3b, v28
	v_mul_f32_e32 v29, 0xbfb8aa3b, v29
	v_exp_f32_e32 v28, v28
	v_exp_f32_e32 v29, v29
	v_add_f32_e32 v28, 1.0, v28
	v_add_f32_e32 v29, 1.0, v29
	v_rcp_f32_e32 v28, v28
	v_rcp_f32_e32 v29, v29
	v_mul_f32_e32 v28, 0xbf60028b, v28
	v_mul_f32_e32 v29, 0xbf60028b, v29
	v_exp_f32_e32 v28, v28
	v_exp_f32_e32 v29, v29
	v_mul_f32_e32 v30, 0xbfb8aa3b, v30
	v_mul_f32_e32 v31, 0xbfb8aa3b, v31
	v_exp_f32_e32 v30, v30
	v_exp_f32_e32 v31, v31
	v_add_f32_e32 v30, 1.0, v30
	v_add_f32_e32 v31, 1.0, v31
	v_rcp_f32_e32 v30, v30
	v_rcp_f32_e32 v31, v31
	v_mul_f32_e32 v30, 0xbf60028b, v30
	v_mul_f32_e32 v31, 0xbf60028b, v31
	v_exp_f32_e32 v30, v30
	v_exp_f32_e32 v31, v31
	v_mul_f32_e32 v24, 0xbfb8aa3b, v24
	v_mul_f32_e32 v25, 0xbfb8aa3b, v25
	v_exp_f32_e32 v24, v24
	v_exp_f32_e32 v25, v25
	v_add_f32_e32 v24, 1.0, v24
	v_add_f32_e32 v25, 1.0, v25
	v_rcp_f32_e32 v24, v24
	v_rcp_f32_e32 v25, v25
	v_mul_f32_e32 v24, 0xbf60028b, v24
	v_mul_f32_e32 v25, 0xbf60028b, v25
	v_exp_f32_e32 v24, v24
	v_exp_f32_e32 v25, v25
	v_mul_f32_e32 v26, 0xbfb8aa3b, v26
	v_mul_f32_e32 v27, 0xbfb8aa3b, v27
	v_exp_f32_e32 v26, v26
	v_exp_f32_e32 v27, v27
	v_add_f32_e32 v26, 1.0, v26
	v_add_f32_e32 v27, 1.0, v27
	v_rcp_f32_e32 v26, v26
	v_rcp_f32_e32 v27, v27
	v_mul_f32_e32 v26, 0xbf60028b, v26
	v_mul_f32_e32 v27, 0xbf60028b, v27
	v_exp_f32_e32 v26, v26
	v_exp_f32_e32 v27, v27
	s_nop 0
	v_or_b32_e32 v104, v104, v74
	v_lshl_add_u64 v[32:33], v[104:105], 2, s[46:47]
	global_store_dwordx4 v[32:33], v[28:31], off
	global_store_dwordx4 v[32:33], v[24:27], off offset:16

;     __device__ __forceinline__ void operator()(const f32x4 (&acc)[2][2][4][2], const pg8::Unit& u, int wr, int wc, int fr, int fq) const {
;     ...
;                     if (kind == 0) {
; #pragma unroll
;                         for (int i = 0; i < 4; ++i) {
;                             { const float z = -v0[i]; const float sp_ = fmaxf(z, 0.f) + __logf(1.f + __expf(-fabsf(z))); v0[i] = __expf(-__expf(-sp_ - 0.5f)); }
;                             { const float z = -v1[i]; const float sp_ = fmaxf(z, 0.f) + __logf(1.f + __expf(-fabsf(z))); v1[i] = __expf(-__expf(-sp_ - 0.5f)); }
;                         }
;                         *(f32x4*)(DEC + off) = v0; *(f32x4*)(DEC + off + 4) = v1;
.LBB0_533:
	s_and_b64 vcc, exec, s[0:1]
	s_cbranch_vccz .LBB0_535
	v_mul_f32_e32 v20, 0xbfb8aa3b, v20
	v_mul_f32_e32 v21, 0xbfb8aa3b, v21
	v_exp_f32_e32 v20, v20
	v_exp_f32_e32 v21, v21
	v_add_f32_e32 v20, 1.0, v20
	v_add_f32_e32 v21, 1.0, v21
	v_rcp_f32_e32 v20, v20
	v_rcp_f32_e32 v21, v21
	v_mul_f32_e32 v20, 0xbf60028b, v20
	v_mul_f32_e32 v21, 0xbf60028b, v21
	v_exp_f32_e32 v20, v20
	v_exp_f32_e32 v21, v21
	v_mul_f32_e32 v22, 0xbfb8aa3b, v22
	v_mul_f32_e32 v23, 0xbfb8aa3b, v23
	v_exp_f32_e32 v22, v22
	v_exp_f32_e32 v23, v23
	v_add_f32_e32 v22, 1.0, v22
	v_add_f32_e32 v23, 1.0, v23
	v_rcp_f32_e32 v22, v22
	v_rcp_f32_e32 v23, v23
	v_mul_f32_e32 v22, 0xbf60028b, v22
	v_mul_f32_e32 v23, 0xbf60028b, v23
	v_exp_f32_e32 v22, v22
	v_exp_f32_e32 v23, v23
	v_mul_f32_e32 v16, 0xbfb8aa3b, v16
	v_mul_f32_e32 v17, 0xbfb8aa3b, v17
	v_exp_f32_e32 v16, v16
	v_exp_f32_e32 v17, v17
	v_add_f32_e32 v16, 1.0, v16
	v_add_f32_e32 v17, 1.0, v17
	v_rcp_f32_e32 v16, v16
	v_rcp_f32_e32 v17, v17
	v_mul_f32_e32 v16, 0xbf60028b, v16
	v_mul_f32_e32 v17, 0xbf60028b, v17
	v_exp_f32_e32 v16, v16
	v_exp_f32_e32 v17, v17
	v_mul_f32_e32 v18, 0xbfb8aa3b, v18
	v_mul_f32_e32 v19, 0xbfb8aa3b, v19
	v_exp_f32_e32 v18, v18
	v_exp_f32_e32 v19, v19
	v_add_f32_e32 v18, 1.0, v18
	v_add_f32_e32 v19, 1.0, v19
	v_rcp_f32_e32 v18, v18
	v_rcp_f32_e32 v19, v19
	v_mul_f32_e32 v18, 0xbf60028b, v18
	v_mul_f32_e32 v19, 0xbf60028b, v19
	v_exp_f32_e32 v18, v18
	v_exp_f32_e32 v19, v19
	s_nop 0
	v_or_b32_e32 v96, v96, v74
	v_lshl_add_u64 v[24:25], v[96:97], 2, s[46:47]
	global_store_dwordx4 v[24:25], v[20:23], off
	global_store_dwordx4 v[24:25], v[16:19], off offset:16

;     __device__ __forceinline__ void operator()(const f32x4 (&acc)[2][2][4][2], const pg8::Unit& u, int wr, int wc, int fr, int fq) const {
;     ...
;                     if (kind == 0) {
; #pragma unroll
;                         for (int i = 0; i < 4; ++i) {
;                             { const float z = -v0[i]; const float sp_ = fmaxf(z, 0.f) + __logf(1.f + __expf(-fabsf(z))); v0[i] = __expf(-__expf(-sp_ - 0.5f)); }
;                             { const float z = -v1[i]; const float sp_ = fmaxf(z, 0.f) + __logf(1.f + __expf(-fabsf(z))); v1[i] = __expf(-__expf(-sp_ - 0.5f)); }
;                         }
;                         *(f32x4*)(DEC + off) = v0; *(f32x4*)(DEC + off + 4) = v1;
.LBB0_539:
	s_and_b64 vcc, exec, s[0:1]
	s_cbranch_vccz .LBB0_541
	v_mul_f32_e32 v12, 0xbfb8aa3b, v12
	v_mul_f32_e32 v13, 0xbfb8aa3b, v13
	v_exp_f32_e32 v12, v12
	v_exp_f32_e32 v13, v13
	v_add_f32_e32 v12, 1.0, v12
	v_add_f32_e32 v13, 1.0, v13
	v_rcp_f32_e32 v12, v12
	v_rcp_f32_e32 v13, v13
	v_mul_f32_e32 v12, 0xbf60028b, v12
	v_mul_f32_e32 v13, 0xbf60028b, v13
	v_exp_f32_e32 v12, v12
	v_exp_f32_e32 v13, v13
	v_mul_f32_e32 v14, 0xbfb8aa3b, v14
	v_mul_f32_e32 v15, 0xbfb8aa3b, v15
	v_exp_f32_e32 v14, v14
	v_exp_f32_e32 v15, v15
	v_add_f32_e32 v14, 1.0, v14
	v_add_f32_e32 v15, 1.0, v15
	v_rcp_f32_e32 v14, v14
	v_rcp_f32_e32 v15, v15
	v_mul_f32_e32 v14, 0xbf60028b, v14
	v_mul_f32_e32 v15, 0xbf60028b, v15
	v_exp_f32_e32 v14, v14
	v_exp_f32_e32 v15, v15
	v_mul_f32_e32 v8, 0xbfb8aa3b, v8
	v_mul_f32_e32 v9, 0xbfb8aa3b, v9
	v_exp_f32_e32 v8, v8
	v_exp_f32_e32 v9, v9
	v_add_f32_e32 v8, 1.0, v8
	v_add_f32_e32 v9, 1.0, v9
	v_rcp_f32_e32 v8, v8
	v_rcp_f32_e32 v9, v9
	v_mul_f32_e32 v8, 0xbf60028b, v8
	v_mul_f32_e32 v9, 0xbf60028b, v9
	v_exp_f32_e32 v8, v8
	v_exp_f32_e32 v9, v9
	v_mul_f32_e32 v10, 0xbfb8aa3b, v10
	v_mul_f32_e32 v11, 0xbfb8aa3b, v11
	v_exp_f32_e32 v10, v10
	v_exp_f32_e32 v11, v11
	v_add_f32_e32 v10, 1.0, v10
	v_add_f32_e32 v11, 1.0, v11
	v_rcp_f32_e32 v10, v10
	v_rcp_f32_e32 v11, v11
	v_mul_f32_e32 v10, 0xbf60028b, v10
	v_mul_f32_e32 v11, 0xbf60028b, v11
	v_exp_f32_e32 v10, v10
	v_exp_f32_e32 v11, v11
	s_nop 0
	v_or_b32_e32 v80, v80, v74
	v_lshl_add_u64 v[16:17], v[80:81], 2, s[46:47]
	global_store_dwordx4 v[16:17], v[12:15], off
	global_store_dwordx4 v[16:17], v[8:11], off offset:16

;     __device__ __forceinline__ void operator()(const f32x4 (&acc)[2][2][4][2], const pg8::Unit& u, int wr, int wc, int fr, int fq) const {
;     ...
;                     if (kind == 0) {
; #pragma unroll
;                         for (int i = 0; i < 4; ++i) {
;                             { const float z = -v0[i]; const float sp_ = fmaxf(z, 0.f) + __logf(1.f + __expf(-fabsf(z))); v0[i] = __expf(-__expf(-sp_ - 0.5f)); }
;                             { const float z = -v1[i]; const float sp_ = fmaxf(z, 0.f) + __logf(1.f + __expf(-fabsf(z))); v1[i] = __expf(-__expf(-sp_ - 0.5f)); }
;                         }
;                         *(f32x4*)(DEC + off) = v0; *(f32x4*)(DEC + off + 4) = v1;
.LBB0_545:
	s_and_b64 vcc, exec, s[0:1]
	s_cbranch_vccz .LBB0_547
	v_mul_f32_e32 v0, 0xbfb8aa3b, v4
	v_mul_f32_e32 v1, 0xbfb8aa3b, v5
	v_exp_f32_e32 v0, v0
	v_exp_f32_e32 v1, v1
	v_add_f32_e32 v0, 1.0, v0
	v_add_f32_e32 v1, 1.0, v1
	v_rcp_f32_e32 v0, v0
	v_rcp_f32_e32 v1, v1
	v_mul_f32_e32 v0, 0xbf60028b, v0
	v_mul_f32_e32 v1, 0xbf60028b, v1
	v_exp_f32_e32 v0, v0
	v_exp_f32_e32 v1, v1
	v_mul_f32_e32 v4, 0xbfb8aa3b, v2
	v_mul_f32_e32 v5, 0xbfb8aa3b, v3
	v_exp_f32_e32 v4, v4
	v_exp_f32_e32 v5, v5
	v_add_f32_e32 v4, 1.0, v4
	v_add_f32_e32 v5, 1.0, v5
	v_rcp_f32_e32 v4, v4
	v_rcp_f32_e32 v5, v5
	v_mul_f32_e32 v4, 0xbf60028b, v4
	v_mul_f32_e32 v5, 0xbf60028b, v5
	v_exp_f32_e32 v4, v4
	v_exp_f32_e32 v5, v5
	v_mul_f32_e32 v6, 0xbfb8aa3b, v6
	v_mul_f32_e32 v7, 0xbfb8aa3b, v7
	v_exp_f32_e32 v6, v6
	v_exp_f32_e32 v7, v7
	v_add_f32_e32 v6, 1.0, v6
	v_add_f32_e32 v7, 1.0, v7
	v_rcp_f32_e32 v6, v6
	v_rcp_f32_e32 v7, v7
	v_mul_f32_e32 v6, 0xbf60028b, v6
	v_mul_f32_e32 v7, 0xbf60028b, v7
	v_exp_f32_e32 v6, v6
	v_exp_f32_e32 v7, v7
	v_mul_f32_e32 v2, 0xbfb8aa3b, v8
	v_mul_f32_e32 v3, 0xbfb8aa3b, v9
	v_exp_f32_e32 v2, v2
	v_exp_f32_e32 v3, v3
	v_add_f32_e32 v2, 1.0, v2
	v_add_f32_e32 v3, 1.0, v3
	v_rcp_f32_e32 v2, v2
	v_rcp_f32_e32 v3, v3
	v_mul_f32_e32 v2, 0xbf60028b, v2
	v_mul_f32_e32 v3, 0xbf60028b, v3
	v_exp_f32_e32 v2, v2
	v_exp_f32_e32 v3, v3
	s_nop 0
	v_or_b32_e32 v72, v72, v74
	v_lshl_add_u64 v[8:9], v[72:73], 2, s[46:47]
	global_store_dwordx4 v[8:9], v[0:3], off
	global_store_dwordx4 v[8:9], v[4:7], off offset:16
